# compiler attention loops (no role split) + cache policies + epilogue de-serialisation + every hot MFMA loop placed inside one 4 KiB code page
# baseline (speedup 1.0000x reference)
; template <int GRP> ...
;     constexpr int DK = GRP == 0 ? 96 : 64, NKS = DK / 16, QP = GRP == 0 ? 768 : 512, NSTEP = 4 * 64;
;     int tid_ = threadIdx.x; asm volatile("" : "+v"(tid_));
;     const int tid = tid_, lane = tid & 63, r32 = lane & 31, hi = lane >> 5, wid = __builtin_amdgcn_readfirstlane(tid >> 6);
;     AttCtx<GRP> C;
;     C.b = b; C.h0 = 4 * hh; C.lds = lds; C.Q = Q; C.KN = KN; C.KPE = KPE; C.VT = VT; C.O = O; C.tid = tid; C.hi = hi; C.trail = false;
;     C.rowbase = (size_t)b * SEQL; C.qrow = C.rowbase + (size_t)qb * 256 + wid * 32 + r32;
;     const int pr = (r32 & 19) | ((r32 & 4) << 1) | ((r32 & 8) >> 1);
;     C.kro = pr * KST + hi * 16; C.vro = 2 * KBUF + r32 * VST + hi * 16;
;     C.kkey = tid >> 3; C.kc = tid & 7; C.pkey = (tid >> 2) & 63; C.pc = tid & 3;
;     { constexpr int NHK = GRP == 0 ? 8 : 2; const size_t lo = (size_t)C.kkey * 64 + C.kc * 8;
;       C.kl = KN + (size_t)(b * NHK) * 64 * 4096 + lo; C.vl = VT + (size_t)(b * NHK) * 64 * 4096 + lo; C.pl = KPE + (C.rowbase + C.pkey) * 32 + C.pc * 8; }
;     C.kwo = C.kkey * KST + C.kc * 16; C.pwo = C.pkey * KST + 128 + C.pc * 16; C.vwo = 2 * KBUF + C.kkey * VST + C.kc * 16;
;     u32x4 kA, pA = {0u, 0u, 0u, 0u}, vA;
;     AttState<GRP> S;
;     S.o0 = (f32x16){}; S.o1 = (f32x16){}; S.mhat = 0.f; S.lrun = 0.f; S.ssq = 0.f; S.refnz = 0;
; #pragma unroll
;     for (int i = 0; i < 16; ++i) S.pw[i] = 0u;
;     { u32x4 kB, pB = {0u, 0u, 0u, 0u};
;       att_ldk<GRP>(C, 0, kA, pA); att_ldk<GRP>(C, 1, kB, pB); att_ldv<GRP>(C, 0, vA);
;       att_stk<GRP>(C, 0, kA, pA); att_stk<GRP>(C, 1, kB, pB); att_stv<GRP>(C, 0, vA); }
;     att_ldk<GRP>(C, 2, kA, pA); att_ldv<GRP>(C, 1, vA);
; #pragma unroll
;     for (int ks = 0; ks < NKS; ++ks) S.qr[ks] = *(const bf16x8*)(Q + C.qrow * QP + C.h0 * DK + ks * 16 + hi * 8);
;     ATT_BAR();
;     f32x16 pa0 = {}, pa1 = {}, pb0 = {}, pb1 = {};
;     {
;         bf16x8 kf[2 * NKS]; att_kfrag<GRP, 0, NKS>(C, 0, kf);
; #pragma unroll
;         for (int ks = 0; ks < NKS; ++ks) { pa0 = __builtin_amdgcn_mfma_f32_32x32x16_bf16(kf[2 * ks], S.qr[ks], pa0, 0, 0, 0); pa1 = __builtin_amdgcn_mfma_f32_32x32x16_bf16(kf[2 * ks + 1], S.qr[ks], pa1, 0, 0, 0); }
;     }
;     if (wid >= 4) __builtin_amdgcn_s_setprio(1);
;     asm volatile("s_nop 15\n\ts_nop 7" : "+v"(pa0), "+v"(pa1));
.LBB0_775:
	v_lshlrev_b32_e32 v4, 3, v2
	s_and_b32 s0, s58, 7
	v_mad_u32_u24 v3, v3, s37, v96
	v_mad_u64_u32 v[6:7], s[14:15], v16, s37, v[18:19]
	v_lshlrev_b32_e32 v96, 1, v4
	s_lshl_b32 s62, s0, 22
	s_lshl_b32 s60, s66, 2
	v_lshl_add_u64 v[164:165], v[0:1], 0, v[96:97]
	v_lshlrev_b64 v[0:1], 7, v[16:17]
	s_lshl_b64 s[14:15], s[10:11], 1
	v_lshlrev_b64 v[8:9], 11, v[152:153]
	v_lshl_add_u64 v[0:1], s[62:63], 0, v[0:1]
	s_add_u32 s14, s8, s14
	v_mov_b32_e32 v5, v97
	v_lshl_add_u64 v[154:155], s[48:49], 0, v[8:9]
	v_lshl_or_b32 v0, v19, 4, v0
	s_addc_u32 s15, s9, s15
	v_mov_b32_e32 v175, 0
	s_mov_b32 s72, 0
	v_cmp_eq_u32_e64 s[0:1], 0, v2
	v_lshlrev_b32_e32 v156, 2, v2
	v_lshl_add_u64 v[162:163], v[154:155], 0, v[4:5]
	v_lshl_add_u64 v[166:167], s[14:15], 0, v[0:1]
	s_add_i32 s70, s10, 0x4000
	s_movk_i32 s67, 0x2000
	v_add_u32_e32 v157, 0, v3
	v_add_u32_e32 v169, 0, v6
	v_mov_b32_e32 v168, 0
	s_mov_b32 s69, 0
	v_mov_b32_e32 v170, 0
	v_mov_b32_e32 v0, 0
	v_mov_b32_e32 v1, v175
	v_mov_b32_e32 v2, v175
	v_mov_b32_e32 v3, v175
	v_mov_b32_e32 v4, v175
	v_mov_b32_e32 v5, v175
	v_mov_b32_e32 v6, v175
	v_mov_b32_e32 v7, v175
	v_mov_b32_e32 v8, v175
	v_mov_b32_e32 v9, v175
	v_mov_b32_e32 v10, v175
	v_mov_b32_e32 v11, v175
	v_mov_b32_e32 v12, v175
	v_mov_b32_e32 v13, v175
	v_mov_b32_e32 v14, v175
	v_mov_b32_e32 v15, v175
	v_mov_b32_e32 v16, 0
	v_mov_b32_e32 v17, v175
	v_mov_b32_e32 v18, v175
	v_mov_b32_e32 v19, v175
	v_mov_b32_e32 v20, v175
	v_mov_b32_e32 v21, v175
	v_mov_b32_e32 v22, v175
	v_mov_b32_e32 v23, v175
	v_mov_b32_e32 v24, v175
	v_mov_b32_e32 v25, v175
	v_mov_b32_e32 v26, v175
	v_mov_b32_e32 v27, v175
	v_mov_b32_e32 v28, v175
	v_mov_b32_e32 v29, v175
	v_mov_b32_e32 v30, v175
	v_mov_b32_e32 v31, v175
	s_nop 15
	s_nop 7
	s_branch .Lpagefit_2
	s_nop 0
	s_nop 0
	s_nop 0
	s_nop 0
	s_nop 0
	s_nop 0
	s_nop 0
	s_nop 0
	s_nop 0
	s_nop 0
	s_nop 0
	s_nop 0
	s_nop 0
	s_nop 0
	s_nop 0
	s_nop 0
	s_nop 0
	s_nop 0
	s_nop 0
	s_nop 0
	s_nop 0
	s_nop 0
	s_nop 0
	s_nop 0
	s_nop 0
	s_nop 0
	s_nop 0
	s_nop 0
	s_nop 0
	s_nop 0
	s_nop 0
	s_nop 0
	s_nop 0
	s_nop 0
	s_nop 0
	s_nop 0
	s_nop 0
	s_nop 0
	s_nop 0
	s_nop 0
	s_nop 0
	s_nop 0
	s_nop 0
	s_nop 0
	s_nop 0
	s_nop 0
	s_nop 0
	s_nop 0
	s_nop 0
	s_nop 0
	s_nop 0
	s_nop 0
	s_nop 0
	s_nop 0
	s_nop 0
	s_nop 0
	s_nop 0
	s_nop 0
	s_nop 0
	s_nop 0
	s_nop 0
	s_nop 0
	s_nop 0
	s_nop 0
	s_nop 0
	s_nop 0
	s_nop 0
	s_nop 0
	s_nop 0
	s_nop 0
	s_nop 0
	s_nop 0
	s_nop 0
	s_nop 0
	s_nop 0
	s_nop 0
	s_nop 0
	s_nop 0
	s_nop 0
	s_nop 0
	s_nop 0
	s_nop 0
	s_nop 0
	s_nop 0
	s_nop 0
	s_nop 0
	s_nop 0
	s_nop 0
	s_nop 0
	s_nop 0
	s_nop 0
	s_nop 0
	s_nop 0
	s_nop 0
	s_nop 0
	s_nop 0
	s_nop 0
	s_nop 0
	s_nop 0
	s_nop 0
	s_nop 0
	s_nop 0
	s_nop 0
	s_nop 0
	s_nop 0
	s_nop 0
	s_nop 0
	s_nop 0
	s_nop 0
	s_nop 0
	s_nop 0
	s_nop 0
	s_nop 0
	s_nop 0
	s_nop 0
	s_nop 0
	s_nop 0
	s_nop 0
	s_nop 0
	s_nop 0
	s_nop 0
	s_nop 0
	s_nop 0
	s_nop 0
	s_nop 0
	s_nop 0
	s_nop 0
	s_nop 0
	s_nop 0
	s_nop 0
	s_nop 0
	s_nop 0
	s_nop 0
	s_nop 0
	s_nop 0
	s_nop 0
	s_nop 0
	s_nop 0
	s_nop 0
	s_nop 0
	s_nop 0
	s_nop 0
	s_nop 0
	s_nop 0
	s_nop 0
	s_nop 0
	s_nop 0
	s_nop 0
	s_nop 0
	s_nop 0
	s_nop 0
	s_nop 0
	s_nop 0
	s_nop 0
	s_nop 0
	s_nop 0
	s_nop 0
	s_nop 0
	s_nop 0
	s_nop 0
	s_nop 0
	s_nop 0
	s_nop 0
	s_nop 0
	s_nop 0
	s_nop 0
	s_nop 0
	s_nop 0
	s_nop 0
	s_nop 0
	s_nop 0
	s_nop 0
	s_nop 0
	s_nop 0
	s_nop 0
	s_nop 0
	s_nop 0
	s_nop 0
	s_nop 0
	s_nop 0
	s_nop 0
	s_nop 0
	s_nop 0
	s_nop 0
	s_nop 0
	s_nop 0
	s_nop 0
	s_nop 0
	s_nop 0
	s_nop 0
	s_nop 0
	s_nop 0
	s_nop 0
	s_nop 0
	s_nop 0
	s_nop 0
	s_nop 0
	s_nop 0
	s_nop 0
	s_nop 0
	s_nop 0
	s_nop 0
	s_nop 0
	s_nop 0
	s_nop 0
	s_nop 0
	s_nop 0
	s_nop 0
	s_nop 0
	s_nop 0
	s_nop 0
	s_nop 0
	s_nop 0
	s_nop 0
	s_nop 0
	s_nop 0
	s_nop 0
	s_nop 0
	s_nop 0
	s_nop 0
	s_nop 0
	s_nop 0
	s_nop 0
	s_nop 0
	s_nop 0
	s_nop 0
	s_nop 0
	s_nop 0
	s_nop 0
	s_nop 0
	s_nop 0
	s_nop 0
	s_nop 0
	s_nop 0
	s_nop 0
	s_nop 0
	s_nop 0
	s_nop 0
	s_nop 0
	s_nop 0
	s_nop 0
	s_nop 0
	s_nop 0
	s_nop 0
	s_nop 0
	s_nop 0
	s_nop 0
	s_nop 0
	s_nop 0
	s_nop 0
	s_nop 0
	s_nop 0
	s_nop 0
	s_nop 0
	s_nop 0
	s_nop 0
	s_nop 0
	s_nop 0
	s_nop 0
	s_nop 0
	s_nop 0
	s_nop 0
	s_nop 0
	s_nop 0
	s_nop 0
	s_nop 0
	s_nop 0
	s_nop 0
	s_nop 0
	s_nop 0
	s_nop 0
	s_nop 0
	s_nop 0
	s_nop 0
	s_nop 0
	s_nop 0
	s_nop 0
	s_nop 0
	s_nop 0
	s_nop 0
	s_nop 0
	s_nop 0
	s_nop 0
	s_nop 0
	s_nop 0
	s_nop 0
	s_nop 0
	s_nop 0
	s_nop 0
	s_nop 0
	s_nop 0
	s_nop 0
	s_nop 0
	s_nop 0
	s_nop 0
	s_nop 0
	s_nop 0
	s_nop 0
	s_nop 0
	s_nop 0
	s_nop 0
	s_nop 0
	s_nop 0
	s_nop 0
	s_nop 0
	s_nop 0
	s_nop 0
	s_nop 0
	s_nop 0
	s_nop 0
	s_nop 0
	s_nop 0
	s_nop 0
	s_nop 0
	s_nop 0
	s_nop 0
	s_nop 0
	s_nop 0
	s_nop 0
	s_nop 0
	s_nop 0
	s_nop 0
	s_nop 0
	s_nop 0
	s_nop 0
	s_nop 0
	s_nop 0
	s_nop 0
	s_nop 0
	s_nop 0
	s_nop 0
	s_nop 0
	s_nop 0
	s_nop 0
	s_nop 0
	s_nop 0
	s_nop 0
	s_nop 0
	s_nop 0
	s_nop 0
	s_nop 0
	s_nop 0
	s_nop 0
	s_nop 0
	s_nop 0
	s_nop 0
	s_nop 0
	s_nop 0
	s_nop 0
	s_nop 0
	s_nop 0
	s_nop 0
	s_nop 0
	s_nop 0
	s_nop 0
	s_nop 0
	s_nop 0
	s_nop 0
	s_nop 0
	s_nop 0
	s_nop 0
	s_nop 0
; __device__ __forceinline__ float xhalf_max(float m) { auto rr = __builtin_amdgcn_permlane32_swap(__float_as_uint(m), __float_as_uint(m), false, false); return fmaxf(__uint_as_float(rr[0]), __uint_as_float(rr[1])); }
; __device__ __forceinline__ float max3f(float a, float b, float c) { float r; asm("v_max3_f32 %0, %1, %2, %3" : "=v"(r) : "v"(a), "v"(b), "v"(c)); return r; }
; __device__ __forceinline__ float max2f(float a, float b) { float r; asm("v_max_f32_e32 %0, %1, %2" : "=v"(r) : "v"(a), "v"(b)); return r; }
; template <int GRP, bool has_next> __device__ __forceinline__ void att_step(const AttCtx<GRP>& C, AttState<GRP>& S, int s, f32x16& P0, f32x16& P1, f32x16& PN0, f32x16& PN1, u32x4& kreg, u32x4& preg, u32x4& vreg) {
;     ...
;         att_kfrag<GRP, 0, NK0>(C, (s + 1) & 1, kfa);
;     }
;     if (has_next) { PN0 = __builtin_amdgcn_mfma_f32_32x32x16_bf16(kfa[0], S.qr[0], (f32x16){}, 0, 0, 0); PN1 = __builtin_amdgcn_mfma_f32_32x32x16_bf16(kfa[1], S.qr[0], (f32x16){}, 0, 0, 0); }
;     if ((t & 7) == 0) {
;         float ma = max3f(P0[0], P0[1], P0[2]), mb = max3f(P0[3], P0[4], P0[5]), mc = max3f(P1[0], P1[1], P1[2]), md = max3f(P1[3], P1[4], P1[5]);
;         ma = max3f(ma, P0[6], P0[7]); mb = max3f(mb, P0[8], P0[9]); mc = max3f(mc, P1[6], P1[7]); md = max3f(md, P1[8], P1[9]);
;         ma = max3f(ma, P0[10], P0[11]); mb = max3f(mb, P0[12], P0[13]); mc = max3f(mc, P1[10], P1[11]); md = max3f(md, P1[12], P1[13]);
;         ma = max3f(ma, P0[14], P0[15]); mc = max3f(mc, P1[14], P1[15]); ma = max3f(ma, mb, mc); mb = md;
;         const float mx = xhalf_max(max2f(ma, mb));
;         const int up = __any(mx > THR), dn = (t == 0) ? __any(mx < -THR) : 0;
	s_nop 0
	s_nop 0
	s_nop 0
	s_nop 0
	s_nop 0
	s_nop 0
	s_nop 0
	s_nop 0
	s_nop 0
	s_nop 0
	s_nop 0
	s_nop 0
	s_nop 0
	s_nop 0
	s_nop 0
	s_nop 0
	s_nop 0
	s_nop 0
	s_nop 0
	s_nop 0
	s_nop 0
	s_nop 0
	s_nop 0
	s_nop 0
	s_nop 0
	s_nop 0
	s_nop 0
	s_nop 0
	s_nop 0
	s_nop 0
	s_nop 0
	s_nop 0
	s_nop 0
	s_nop 0
	s_nop 0
	s_nop 0
	s_nop 0
	s_nop 0
	s_nop 0
	s_nop 0
	s_nop 0
	s_nop 0
	s_nop 0
	s_nop 0
	s_nop 0
	s_nop 0
	s_nop 0
	s_nop 0
	s_nop 0
	s_nop 0
	s_nop 0
	s_nop 0
	s_nop 0
	s_nop 0
	s_nop 0
	s_nop 0
	s_nop 0
	s_nop 0
	s_nop 0
	s_nop 0
	s_nop 0
	s_nop 0
	s_nop 0
	s_nop 0
	s_nop 0
	s_nop 0
	s_nop 0
	s_nop 0
	s_nop 0
	s_nop 0
	s_nop 0
	s_nop 0
	s_nop 0
	s_nop 0
	s_nop 0
	s_nop 0
	s_nop 0
	s_nop 0
	s_nop 0
	s_nop 0
	s_nop 0
	s_nop 0
	s_nop 0
	s_nop 0
	s_nop 0
	s_nop 0
	s_nop 0
	s_nop 0
	s_nop 0
	s_nop 0
	s_nop 0
	s_nop 0
	s_nop 0
	s_nop 0
	s_nop 0
	s_nop 0
	s_nop 0
	s_nop 0
	s_nop 0
	s_nop 0
	s_nop 0
	s_nop 0
	s_nop 0
	s_nop 0
	s_nop 0
	s_nop 0
	s_nop 0
	s_nop 0
	s_nop 0
	s_nop 0
	s_nop 0
	s_nop 0
	s_nop 0
	s_nop 0
	s_nop 0
	s_nop 0
	s_nop 0
	s_nop 0
	s_nop 0
	s_nop 0
	s_nop 0
	s_nop 0
	s_nop 0
	s_nop 0
	s_nop 0
	s_nop 0
	s_nop 0
	s_nop 0
	s_nop 0
	s_nop 0
	s_nop 0
	s_nop 0
	s_nop 0
	s_nop 0
	s_nop 0
	s_nop 0
	s_nop 0
	s_nop 0
	s_nop 0
	s_nop 0
	s_nop 0
	s_nop 0
	s_nop 0
	s_nop 0
	s_nop 0
	s_nop 0
	s_nop 0
	s_nop 0
	s_nop 0
	s_nop 0
	s_nop 0
	s_nop 0
	s_nop 0
	s_nop 0
	s_nop 0
	s_nop 0
	s_nop 0
	s_nop 0
	s_nop 0
	s_nop 0
	s_nop 0
	s_nop 0
	s_nop 0
	s_nop 0
	s_nop 0
	s_nop 0
	s_nop 0
	s_nop 0
	s_nop 0
	s_nop 0
	s_nop 0
	s_nop 0
	s_nop 0
	s_nop 0
	s_nop 0
	s_nop 0
	s_nop 0
	s_nop 0
	s_nop 0
	s_nop 0
	s_nop 0
	s_nop 0
	s_nop 0
	s_nop 0
	s_nop 0
	s_nop 0
	s_nop 0
	s_nop 0
	s_nop 0
	s_nop 0
	s_nop 0
	s_nop 0
	s_nop 0
	s_nop 0
	s_nop 0
	s_nop 0
	s_nop 0
	s_nop 0
	s_nop 0
	s_nop 0
	s_nop 0
	s_nop 0
	s_nop 0
	s_nop 0
	s_nop 0
	s_nop 0
	s_nop 0
	s_nop 0
	s_nop 0
	s_nop 0
	s_nop 0
	s_nop 0
	s_nop 0
	s_nop 0
	s_nop 0
	s_nop 0
	s_nop 0
	s_nop 0
	s_nop 0
	s_nop 0
	s_nop 0
	s_nop 0
	s_nop 0
	s_nop 0
	s_nop 0
	s_nop 0
	s_nop 0
	s_nop 0
	s_nop 0
	s_nop 0
	s_nop 0
	s_nop 0
	s_nop 0
	s_nop 0
	s_nop 0
	s_nop 0
	s_nop 0
	s_nop 0
	s_nop 0
	s_nop 0
	s_nop 0
	s_nop 0
	s_nop 0
	s_nop 0
	s_nop 0
	s_nop 0
	s_nop 0
	s_nop 0
	s_nop 0
	s_nop 0
	s_nop 0
	s_nop 0
	s_nop 0
	s_nop 0
	s_nop 0
	s_nop 0
	s_nop 0
	s_nop 0
	s_nop 0
	s_nop 0
	s_nop 0
	s_nop 0
	s_nop 0
	s_nop 0
	s_nop 0
	s_nop 0
	s_nop 0
	s_nop 0
	s_nop 0
	s_nop 0
	s_nop 0
	s_nop 0
	s_nop 0
	s_nop 0
	s_nop 0
	s_nop 0
	s_nop 0
	s_nop 0
	s_nop 0
	s_nop 0
	s_nop 0
	s_nop 0
	s_nop 0
	s_nop 0
	s_nop 0
	s_nop 0
	s_nop 0
	s_nop 0
	s_nop 0
	s_nop 0
	s_nop 0
	s_nop 0
	s_nop 0
	s_nop 0
	s_nop 0
	s_nop 0
	s_nop 0
	s_nop 0
	s_nop 0
	s_nop 0
	s_nop 0
	s_nop 0
	s_nop 0
	s_nop 0
	s_nop 0
	s_nop 0
	s_nop 0
	s_nop 0
	s_nop 0
	s_nop 0
	s_nop 0
	s_nop 0
	s_nop 0
	s_nop 0
	s_nop 0
	s_nop 0
	s_nop 0
	s_nop 0
	s_nop 0
	s_nop 0
	s_nop 0
	s_nop 0
	s_nop 0
	s_nop 0
	s_nop 0
	s_nop 0
	s_nop 0
	s_nop 0
	s_nop 0
	s_nop 0
	s_nop 0
	s_nop 0
	s_nop 0
	s_nop 0
	s_nop 0
	s_nop 0
	s_nop 0
	s_nop 0
	s_nop 0
	s_nop 0
	s_nop 0
	s_nop 0
	s_nop 0
	s_nop 0
	s_nop 0
	s_nop 0
	s_nop 0
	s_nop 0
	s_nop 0
	s_nop 0
	s_nop 0
	s_nop 0
	s_nop 0
	s_nop 0
	s_nop 0
	s_nop 0
	s_nop 0
	s_nop 0
	s_nop 0
	s_nop 0
	s_nop 0
	s_nop 0
	s_nop 0
	s_nop 0
	s_nop 0
	s_nop 0
	s_nop 0
	s_nop 0
	s_nop 0
	s_nop 0
	s_nop 0
	s_nop 0
	s_nop 0
	s_nop 0
	s_nop 0
	s_nop 0
	s_nop 0
	s_nop 0
	s_nop 0
	s_nop 0
	s_nop 0
	s_nop 0
	s_nop 0
	s_nop 0
	s_nop 0
	s_nop 0
	s_nop 0
	s_nop 0
	s_nop 0
	s_nop 0
	s_nop 0
.Lpagefit_2:
.LBB0_776:
	ds_read_b128 v[64:67], v174 offset:13312
	ds_read_b128 v[136:139], v174 offset:13344
	s_and_b32 s10, s69, 6
	s_cmp_lg_u32 s10, 0
	s_waitcnt lgkmcnt(1)
	v_mfma_f32_32x32x16_bf16 v[80:95], v[64:67], v[128:131], 0
	ds_read_b128 v[64:67], v174 offset:19968
	ds_read_b128 v[140:143], v174 offset:13376
	ds_read_b128 v[148:151], v174 offset:20000
	ds_read_b128 v[144:147], v174 offset:20032
	s_waitcnt lgkmcnt(3)
	v_mfma_f32_32x32x16_bf16 v[64:79], v[64:67], v[128:131], 0
	s_cbranch_scc1 .LBB0_781
	v_max3_f32 v96, v48, v49, v50
	v_max3_f32 v99, v32, v33, v34
	v_max3_f32 v98, v51, v52, v53
	v_max3_f32 v176, v35, v36, v37
	s_and_b32 s14, s69, 56
	v_max3_f32 v96, v96, v54, v55
	v_max3_f32 v99, v99, v38, v39
	v_max3_f32 v98, v98, v56, v57
	v_max3_f32 v176, v176, v40, v41
	s_cmp_eq_u32 s14, 0
	v_max3_f32 v96, v96, v58, v59
	v_max3_f32 v99, v99, v42, v43
	v_max3_f32 v98, v98, v60, v61
	v_max3_f32 v176, v176, v44, v45
	s_cselect_b64 s[10:11], -1, 0
	v_max3_f32 v96, v96, v62, v63
	v_max3_f32 v99, v99, v46, v47
	s_cmp_lg_u32 s14, 0
	v_max3_f32 v96, v96, v98, v99
	s_nop 0
	v_max_f32_e32 v96, v96, v176
	s_nop 0
	v_mov_b32_e32 v98, v96
	s_nop 1
	v_permlane32_swap_b32_e32 v96, v98
	v_max_f32_e32 v98, v98, v98
	v_max_f32_e32 v96, v96, v96
	v_max_f32_e32 v96, v96, v98
	v_cmp_lt_f32_e32 vcc, s54, v96
	v_mov_b32_e32 v98, 0
	s_cbranch_scc1 .LBB0_779
	v_cmp_gt_f32_e64 s[14:15], s55, v96
	s_cmp_lg_u64 s[14:15], 0
	s_cselect_b64 s[14:15], -1, 0
	v_cndmask_b32_e64 v98, 0, 1, s[14:15]

; template <int GRP> ...
;     constexpr int DK = GRP == 0 ? 96 : 64, NKS = DK / 16, QP = GRP == 0 ? 768 : 512, NSTEP = 4 * 64;
;     int tid_ = threadIdx.x; asm volatile("" : "+v"(tid_));
;     const int tid = tid_, lane = tid & 63, r32 = lane & 31, hi = lane >> 5, wid = __builtin_amdgcn_readfirstlane(tid >> 6);
;     AttCtx<GRP> C;
;     C.b = b; C.h0 = 4 * hh; C.lds = lds; C.Q = Q; C.KN = KN; C.KPE = KPE; C.VT = VT; C.O = O; C.tid = tid; C.hi = hi; C.trail = false;
;     C.rowbase = (size_t)b * SEQL; C.qrow = C.rowbase + (size_t)qb * 256 + wid * 32 + r32;
;     const int pr = (r32 & 19) | ((r32 & 4) << 1) | ((r32 & 8) >> 1);
;     C.kro = pr * KST + hi * 16; C.vro = 2 * KBUF + r32 * VST + hi * 16;
;     C.kkey = tid >> 3; C.kc = tid & 7; C.pkey = (tid >> 2) & 63; C.pc = tid & 3;
;     { constexpr int NHK = GRP == 0 ? 8 : 2; const size_t lo = (size_t)C.kkey * 64 + C.kc * 8;
;       C.kl = KN + (size_t)(b * NHK) * 64 * 4096 + lo; C.vl = VT + (size_t)(b * NHK) * 64 * 4096 + lo; C.pl = KPE + (C.rowbase + C.pkey) * 32 + C.pc * 8; }
;     C.kwo = C.kkey * KST + C.kc * 16; C.pwo = C.pkey * KST + 128 + C.pc * 16; C.vwo = 2 * KBUF + C.kkey * VST + C.kc * 16;
;     u32x4 kA, pA = {0u, 0u, 0u, 0u}, vA;
;     AttState<GRP> S;
;     S.o0 = (f32x16){}; S.o1 = (f32x16){}; S.mhat = 0.f; S.lrun = 0.f; S.ssq = 0.f; S.refnz = 0;
; #pragma unroll
;     for (int i = 0; i < 16; ++i) S.pw[i] = 0u;
;     { u32x4 kB, pB = {0u, 0u, 0u, 0u};
;       att_ldk<GRP>(C, 0, kA, pA); att_ldk<GRP>(C, 1, kB, pB); att_ldv<GRP>(C, 0, vA);
;       att_stk<GRP>(C, 0, kA, pA); att_stk<GRP>(C, 1, kB, pB); att_stv<GRP>(C, 0, vA); }
;     att_ldk<GRP>(C, 2, kA, pA); att_ldv<GRP>(C, 1, vA);
; #pragma unroll
;     for (int ks = 0; ks < NKS; ++ks) S.qr[ks] = *(const bf16x8*)(Q + C.qrow * QP + C.h0 * DK + ks * 16 + hi * 8);
;     ATT_BAR();
;     f32x16 pa0 = {}, pa1 = {}, pb0 = {}, pb1 = {};
;     {
;         bf16x8 kf[2 * NKS]; att_kfrag<GRP, 0, NKS>(C, 0, kf);
; #pragma unroll
;         for (int ks = 0; ks < NKS; ++ks) { pa0 = __builtin_amdgcn_mfma_f32_32x32x16_bf16(kf[2 * ks], S.qr[ks], pa0, 0, 0, 0); pa1 = __builtin_amdgcn_mfma_f32_32x32x16_bf16(kf[2 * ks + 1], S.qr[ks], pa1, 0, 0, 0); }
;     }
;     if (wid >= 4) __builtin_amdgcn_s_setprio(1);
;     asm volatile("s_nop 15\n\ts_nop 7" : "+v"(pa0), "+v"(pa1));
.LBB0_807:
	v_lshlrev_b32_e32 v8, 3, v3
	v_mad_u32_u24 v10, v6, s37, v96
	v_lshlrev_b64 v[6:7], 11, v[132:133]
	v_mov_b32_e32 v9, v97
	v_mad_u64_u32 v[0:1], s[6:7], v0, s37, v[2:3]
	v_lshl_add_u64 v[134:135], s[48:49], 0, v[6:7]
	v_lshlrev_b32_e32 v96, 1, v8
	v_mov_b32_e32 v152, 0
	s_mov_b32 s62, 0
	v_cmp_eq_u32_e64 s[0:1], 0, v3
	v_lshlrev_b32_e32 v136, 2, v3
	v_lshl_add_u64 v[142:143], v[134:135], 0, v[8:9]
	v_lshl_add_u64 v[144:145], v[4:5], 0, v[96:97]
	v_add_u32_e32 v146, 0, v10
	v_add_u32_e32 v147, 0, v0
	v_mov_b32_e32 v137, 0
	s_mov_b32 s61, 0
	v_mov_b32_e32 v148, 0
	v_mov_b32_e32 v0, 0
	v_mov_b32_e32 v1, v152
	v_mov_b32_e32 v2, v152
	v_mov_b32_e32 v3, v152
	v_mov_b32_e32 v4, v152
	v_mov_b32_e32 v5, v152
	v_mov_b32_e32 v6, v152
	v_mov_b32_e32 v7, v152
	v_mov_b32_e32 v8, v152
	v_mov_b32_e32 v9, v152
	v_mov_b32_e32 v10, v152
	v_mov_b32_e32 v11, v152
	v_mov_b32_e32 v12, v152
	v_mov_b32_e32 v13, v152
	v_mov_b32_e32 v14, v152
	v_mov_b32_e32 v15, v152
	v_mov_b32_e32 v16, 0
	v_mov_b32_e32 v17, v152
	v_mov_b32_e32 v18, v152
	v_mov_b32_e32 v19, v152
	v_mov_b32_e32 v20, v152
	v_mov_b32_e32 v21, v152
	v_mov_b32_e32 v22, v152
	v_mov_b32_e32 v23, v152
	v_mov_b32_e32 v24, v152
	v_mov_b32_e32 v25, v152
	v_mov_b32_e32 v26, v152
	v_mov_b32_e32 v27, v152
	v_mov_b32_e32 v28, v152
	v_mov_b32_e32 v29, v152
	v_mov_b32_e32 v30, v152
	v_mov_b32_e32 v31, v152
	s_nop 15
	s_nop 7
	s_branch .Lpagefit_3
	s_nop 0
	s_nop 0
	s_nop 0
	s_nop 0
	s_nop 0
	s_nop 0
	s_nop 0
	s_nop 0
	s_nop 0
	s_nop 0
	s_nop 0
	s_nop 0
	s_nop 0
	s_nop 0
	s_nop 0
	s_nop 0
	s_nop 0
	s_nop 0
	s_nop 0
	s_nop 0
	s_nop 0
	s_nop 0
	s_nop 0
	s_nop 0
	s_nop 0
	s_nop 0
	s_nop 0
	s_nop 0
	s_nop 0
	s_nop 0
	s_nop 0
	s_nop 0
	s_nop 0
	s_nop 0
	s_nop 0
	s_nop 0
	s_nop 0
	s_nop 0
	s_nop 0
	s_nop 0
	s_nop 0
	s_nop 0
	s_nop 0
	s_nop 0
	s_nop 0
	s_nop 0
	s_nop 0
	s_nop 0
	s_nop 0
	s_nop 0
	s_nop 0
	s_nop 0
	s_nop 0
	s_nop 0
	s_nop 0
	s_nop 0
	s_nop 0
	s_nop 0
	s_nop 0
	s_nop 0
	s_nop 0
	s_nop 0
	s_nop 0
	s_nop 0
	s_nop 0
	s_nop 0
	s_nop 0
	s_nop 0
	s_nop 0
	s_nop 0
	s_nop 0
	s_nop 0
	s_nop 0
	s_nop 0
	s_nop 0
	s_nop 0
	s_nop 0
	s_nop 0
	s_nop 0
	s_nop 0
	s_nop 0
	s_nop 0
	s_nop 0
	s_nop 0
	s_nop 0
	s_nop 0
	s_nop 0
	s_nop 0
	s_nop 0
	s_nop 0
	s_nop 0
	s_nop 0
	s_nop 0
	s_nop 0
	s_nop 0
	s_nop 0
	s_nop 0
	s_nop 0
	s_nop 0
	s_nop 0
	s_nop 0
	s_nop 0
	s_nop 0
	s_nop 0
	s_nop 0
	s_nop 0
	s_nop 0
	s_nop 0
	s_nop 0
	s_nop 0
	s_nop 0
	s_nop 0
	s_nop 0
	s_nop 0
	s_nop 0
	s_nop 0
	s_nop 0
	s_nop 0
	s_nop 0
	s_nop 0
	s_nop 0
	s_nop 0
	s_nop 0
	s_nop 0
	s_nop 0
	s_nop 0
	s_nop 0
	s_nop 0
	s_nop 0
	s_nop 0
	s_nop 0
	s_nop 0
	s_nop 0
	s_nop 0
	s_nop 0
	s_nop 0
	s_nop 0
	s_nop 0
	s_nop 0
	s_nop 0
	s_nop 0
	s_nop 0
	s_nop 0
	s_nop 0
	s_nop 0
	s_nop 0
	s_nop 0
	s_nop 0
	s_nop 0
	s_nop 0
	s_nop 0
	s_nop 0
	s_nop 0
	s_nop 0
	s_nop 0
	s_nop 0
	s_nop 0
	s_nop 0
	s_nop 0
	s_nop 0
	s_nop 0
	s_nop 0
	s_nop 0
	s_nop 0
	s_nop 0
	s_nop 0
	s_nop 0
	s_nop 0
	s_nop 0
	s_nop 0
	s_nop 0
	s_nop 0
	s_nop 0
	s_nop 0
	s_nop 0
	s_nop 0
	s_nop 0
	s_nop 0
	s_nop 0
	s_nop 0
	s_nop 0
	s_nop 0
	s_nop 0
	s_nop 0
	s_nop 0
	s_nop 0
	s_nop 0
	s_nop 0
	s_nop 0
	s_nop 0
	s_nop 0
	s_nop 0
	s_nop 0
	s_nop 0
	s_nop 0
	s_nop 0
	s_nop 0
	s_nop 0
	s_nop 0
	s_nop 0
	s_nop 0
	s_nop 0
	s_nop 0
	s_nop 0
	s_nop 0
	s_nop 0
	s_nop 0
	s_nop 0
	s_nop 0
	s_nop 0
	s_nop 0
	s_nop 0
	s_nop 0
	s_nop 0
	s_nop 0
	s_nop 0
	s_nop 0
	s_nop 0
	s_nop 0
	s_nop 0
	s_nop 0
	s_nop 0
	s_nop 0
	s_nop 0
	s_nop 0
	s_nop 0
	s_nop 0
	s_nop 0
	s_nop 0
	s_nop 0
	s_nop 0
	s_nop 0
	s_nop 0
	s_nop 0
	s_nop 0
	s_nop 0
	s_nop 0
	s_nop 0
	s_nop 0
	s_nop 0
	s_nop 0
	s_nop 0
	s_nop 0
	s_nop 0
	s_nop 0
	s_nop 0
	s_nop 0
	s_nop 0
	s_nop 0
	s_nop 0
	s_nop 0
	s_nop 0
	s_nop 0
	s_nop 0
	s_nop 0
	s_nop 0
	s_nop 0
	s_nop 0
	s_nop 0
	s_nop 0
	s_nop 0
	s_nop 0
	s_nop 0
	s_nop 0
	s_nop 0
	s_nop 0
	s_nop 0
	s_nop 0
	s_nop 0
	s_nop 0
	s_nop 0
	s_nop 0
	s_nop 0
	s_nop 0
	s_nop 0
	s_nop 0
	s_nop 0
	s_nop 0
	s_nop 0
	s_nop 0
	s_nop 0
	s_nop 0
	s_nop 0
	s_nop 0
	s_nop 0
	s_nop 0
	s_nop 0
	s_nop 0
	s_nop 0
	s_nop 0
	s_nop 0
	s_nop 0
	s_nop 0
	s_nop 0
	s_nop 0
	s_nop 0
	s_nop 0
	s_nop 0
	s_nop 0
	s_nop 0
	s_nop 0
	s_nop 0
	s_nop 0
	s_nop 0
	s_nop 0
	s_nop 0
	s_nop 0
	s_nop 0
	s_nop 0
	s_nop 0
	s_nop 0
	s_nop 0
	s_nop 0
	s_nop 0
	s_nop 0
	s_nop 0
	s_nop 0
	s_nop 0
	s_nop 0
	s_nop 0
	s_nop 0
	s_nop 0
	s_nop 0
	s_nop 0
	s_nop 0
	s_nop 0
	s_nop 0
	s_nop 0
	s_nop 0
	s_nop 0
	s_nop 0
	s_nop 0
	s_nop 0
	s_nop 0
	s_nop 0
	s_nop 0
	s_nop 0
	s_nop 0
	s_nop 0
	s_nop 0
	s_nop 0
	s_nop 0
	s_nop 0
	s_nop 0
	s_nop 0
	s_nop 0
	s_nop 0
	s_nop 0
	s_nop 0
	s_nop 0
	s_nop 0
	s_nop 0
	s_nop 0
	s_nop 0
	s_nop 0
	s_nop 0
	s_nop 0
	s_nop 0
	s_nop 0
	s_nop 0
	s_nop 0
	s_nop 0
	s_nop 0
	s_nop 0
	s_nop 0
	s_nop 0
	s_nop 0
	s_nop 0
	s_nop 0
	s_nop 0
	s_nop 0
	s_nop 0
	s_nop 0
.Lpagefit_3:
.LBB0_808:
	ds_read_b128 v[64:67], v149 offset:13312
	ds_read_b128 v[124:127], v149 offset:13344
	s_and_b32 s6, s61, 6
	s_cmp_lg_u32 s6, 0
	s_waitcnt lgkmcnt(1)
	v_mfma_f32_32x32x16_bf16 v[80:95], v[64:67], v[112:115], 0
	ds_read_b128 v[64:67], v149 offset:19968
	ds_read_b128 v[128:131], v149 offset:20000
	s_waitcnt lgkmcnt(1)
	v_mfma_f32_32x32x16_bf16 v[64:79], v[64:67], v[112:115], 0
	s_cbranch_scc1 .LBB0_813
	v_max3_f32 v96, v48, v49, v50
	v_max3_f32 v99, v32, v33, v34
	v_max3_f32 v98, v51, v52, v53
	v_max3_f32 v153, v35, v36, v37
	s_and_b32 s10, s61, 56
	v_max3_f32 v96, v96, v54, v55
	v_max3_f32 v99, v99, v38, v39
	v_max3_f32 v98, v98, v56, v57
	v_max3_f32 v153, v153, v40, v41
	s_cmp_eq_u32 s10, 0
	v_max3_f32 v96, v96, v58, v59
	v_max3_f32 v99, v99, v42, v43
	v_max3_f32 v98, v98, v60, v61
	v_max3_f32 v153, v153, v44, v45
	s_cselect_b64 s[6:7], -1, 0
	v_max3_f32 v96, v96, v62, v63
	v_max3_f32 v99, v99, v46, v47
	s_cmp_lg_u32 s10, 0
	v_max3_f32 v96, v96, v98, v99
	s_nop 0
	v_max_f32_e32 v96, v96, v153
	s_nop 0
	v_mov_b32_e32 v98, v96
	s_nop 1
	v_permlane32_swap_b32_e32 v96, v98
	v_max_f32_e32 v98, v98, v98
	v_max_f32_e32 v96, v96, v96
	v_max_f32_e32 v96, v96, v98
	v_cmp_lt_f32_e32 vcc, s54, v96
	v_mov_b32_e32 v98, 0
	s_cbranch_scc1 .LBB0_811
	v_cmp_gt_f32_e64 s[10:11], s55, v96
	s_cmp_lg_u64 s[10:11], 0
	s_cselect_b64 s[10:11], -1, 0
	v_cndmask_b32_e64 v98, 0, 1, s[10:11]
